# static s_setprio 1 for waves 4-7 across the whole merge phase (reset before the phase-end barrier)
# speedup vs baseline: 1.0073x; 1.0019x over previous
; DI int otid() { int t = threadIdx.x; asm volatile("" : "+v"(t)); return t; }
; DI void phase_merge(const bf16_t* __restrict__ xn, const bf16_t* __restrict__ Wl, const bf16_t* __restrict__ ya, const bf16_t* __restrict__ yn, const bf16_t* __restrict__ yd,
;                     bf16_t* __restrict__ mo, unsigned char* smem) {
;   const int tid_ = otid(), lane = tid_ & 63, w = tid_ >> 6, wr = w >> 1, wc = w & 1, fr = lane & 15, fq = lane >> 4;
;   constexpr int nN = D / 128, nM = HT / 256;
;   for (int id = blockIdx.x; id < nM * nN; id += gridDim.x) {
;     int pm, pn; tile_coords(id, nN, pm, pn);
;     unsigned tot[4][4][2];
; #pragma unroll 1
;     for (int i = 0; i < 3; ++i) {
;       unsigned gp[4][4][2];
;       {
;         f32x4 ag[4][4]; zero_acc(ag);
;         const bf16_t* Yn = (i == 0) ? ya : (i == 1 ? yn : yd);
;         const int Kn = (i == 0) ? 512 : 256;
;         const bf16_t* Pn = Wl + (i == 0 ? W_PA : (i == 1 ? W_PB : W_PC));
;         gemm_block<4, 4, 4, 2>(xn + (size_t)pm * 256 * D, D, Wl + W_IN + (size_t)(ZC + i * 1024 + pn * 128) * D, D, D, ag, smem, !(i == 0 && id == (int)blockIdx.x),
.LBB0_646:
	s_or_b64 exec, exec, s[0:1]
	v_readlane_b32 s0, v253, 33
	v_readlane_b32 s1, v253, 34
	s_waitcnt lgkmcnt(0)
	v_mov_b32_e32 v0, v212
	s_andn2_b64 vcc, exec, s[0:1]
	s_barrier
	s_cbranch_vccnz .LBB0_705
	v_readfirstlane_b32 s98, v0
	s_cmp_lt_u32 s98, 0x100
	s_cbranch_scc1 .Lmprio
	s_setprio 1
.Lmprio:
	v_ashrrev_i32_e32 v2, 1, v0
	v_readlane_b32 s4, v252, 0
	v_and_b32_e32 v1, 64, v0
	v_and_b32_e32 v2, 0xffffffc0, v2
	v_readlane_b32 s5, v252, 1
	v_and_or_b32 v132, v0, 15, v2
	v_lshlrev_b32_e32 v128, 1, v1
	v_lshrrev_b32_e32 v0, 1, v0
	v_readlane_b32 s6, v252, 2
	s_mov_b64 s[0:1], s[4:5]
	v_ashrrev_i32_e32 v133, 31, v2
	v_lshl_add_u64 v[2:3], s[52:53], 0, v[128:129]
	v_and_b32_e32 v128, 24, v0
	s_mov_b32 s2, s6
	s_add_u32 s89, s0, s77
	s_waitcnt vmcnt(5)
	v_lshl_add_u64 v[134:135], v[2:3], 0, v[128:129]
	s_addc_u32 s94, s1, 0
	s_mov_b32 s2, s92
	v_readlane_b32 s7, v252, 3
	s_waitcnt vmcnt(0)
	s_branch .LBB0_649

; DI void xcd_barrier(const XcdBarrier& b) {
;   asm volatile("s_waitcnt vmcnt(0)" ::: "memory");
;   __syncthreads();
;   if (threadIdx.x == 0) {
;     unsigned* bar = b.bar;
;     __builtin_amdgcn_s_waitcnt(0);
;     unsigned nloc = b.st[0], nx = b.st[1];
;     if (nloc == 0u) { xcd_barrier_complete(bar, b.x, nloc, nx); b.st[0] = nloc; b.st[1] = nx; }
.LBB0_705:
	s_setprio 0
	s_waitcnt vmcnt(0)
	s_waitcnt vmcnt(0) lgkmcnt(0)
	s_barrier
	s_mov_b64 s[0:1], exec
	v_readlane_b32 s4, v252, 6
	v_readlane_b32 s5, v252, 7
	s_and_b64 s[4:5], s[0:1], s[4:5]
	s_mov_b64 exec, s[4:5]
	s_cbranch_execz .LBB0_757
	s_waitcnt vmcnt(0) expcnt(0) lgkmcnt(0)
	ds_read_b32 v2, v216
	ds_read_b32 v0, v217
	s_waitcnt lgkmcnt(1)
	v_cmp_ne_u32_e32 vcc, 0, v2
	s_cbranch_vccnz .LBB0_721
	s_mov_b32 s2, 1
	s_branch .LBB0_709
